# nt also on gdn-prep conv-window (Z) loads; cumulative nt: scan records/U, conversion + w_ada weight loads, prep Z
# speedup vs baseline: 1.0185x; 1.0036x over previous
; __device__ __forceinline__ void gdn_prep_phase(const Frame& F0, const Args& a0, int l) {
;     ...
;     if (F.vcu < NB * 8 * 36) GD_PREFETCH(F.vcu);
.LBB0_378:
	s_mul_hi_i32 s4, s27, 0x38e38e39
	s_ashr_i32 s5, s4, 3
	s_lshr_b32 s16, s4, 31
	s_add_i32 s5, s5, s16
	s_mul_i32 s15, s5, 36
	s_lshr_b32 s4, s4, 6
	s_sub_i32 s17, s27, s15
	s_add_i32 s4, s4, s16
	s_mul_i32 s16, s4, 0x900
	s_lshl_b32 s4, s17, 6
	s_and_b32 s15, s5, 7
	s_add_i32 s16, s16, s4
	s_add_i32 s5, s4, 0xffffff00
	s_cmp_lt_i32 s17, 4
	s_movk_i32 s17, 0x7ff
	v_lshlrev_b32_e32 v0, 10, v0
	v_lshlrev_b32_e32 v1, 2, v23
	s_cselect_b32 s17, 0xff, s17
	s_cselect_b32 s4, s4, s5
	v_cndmask_b32_e64 v0, v188, v0, s[2:3]
	s_lshl_b32 s5, s15, 7
	v_and_b32_e32 v1, 0x7c, v1
	v_or3_b32 v20, v0, s5, v1
	v_ashrrev_i32_e32 v21, 31, v20
	v_lshl_add_u64 v[16:17], v[20:21], 2, s[62:63]
	s_movk_i32 s5, 0x3000
	v_add_co_u32_e32 v4, vcc, s5, v16
	s_movk_i32 s5, 0x6000
	s_nop 0
	v_addc_co_u32_e32 v5, vcc, 0, v17, vcc
	v_add_co_u32_e32 v8, vcc, s5, v16
	s_mov_b32 s5, 0x9000
	s_nop 0
	v_addc_co_u32_e32 v9, vcc, 0, v17, vcc
	v_add_co_u32_e32 v12, vcc, s5, v16
	s_mov_b32 s5, 0xc000
	s_nop 0
	v_addc_co_u32_e32 v13, vcc, 0, v17, vcc
	global_load_dwordx4 v[0:3], v[16:17], off
	s_nop 0
	global_load_dwordx4 v[4:7], v[4:5], off
	v_add_co_u32_e32 v16, vcc, s5, v16
	v_add_u32_e32 v24, s4, v24
	s_nop 0
	v_addc_co_u32_e32 v17, vcc, 0, v17, vcc
	v_add_u32_e32 v25, -2, v24
	v_min_i32_e32 v25, s17, v25
	v_cmp_lt_i32_e32 vcc, 1, v24
	s_sub_i32 s18, s16, s4
	v_mov_b64_e32 v[26:27], s[76:77]
	v_cndmask_b32_e32 v25, 0, v25, vcc
	v_add_u32_e32 v25, s18, v25
	v_mad_i64_i32 v[28:29], s[4:5], v25, s87, v[26:27]
	v_or_b32_e32 v25, 1, v24
	v_add_u32_e32 v32, -1, v24
	v_min_i32_e32 v32, s17, v32
	v_cmp_lt_i32_e32 vcc, 1, v25
	v_min_i32_e32 v25, s17, v25
	v_min_i32_e32 v34, s17, v24
	v_cndmask_b32_e32 v32, 0, v32, vcc
	v_cmp_gt_i32_e32 vcc, 0, v24
	v_lshlrev_b64 v[30:31], 1, v[20:21]
	v_add_u32_e32 v32, s18, v32
	v_cndmask_b32_e64 v25, v25, 0, vcc
	v_add_u32_e32 v25, s18, v25
	v_mad_i64_i32 v[36:37], s[4:5], v25, s87, v[26:27]
	v_or_b32_e32 v25, 2, v24
	v_cndmask_b32_e64 v34, v34, 0, vcc
	v_min_i32_e32 v25, s17, v25
	v_add_u32_e32 v34, s18, v34
	v_cndmask_b32_e64 v25, v25, 0, vcc
	v_lshl_add_u64 v[28:29], v[28:29], 0, v[30:31]
	v_mad_i64_i32 v[32:33], s[4:5], v32, s87, v[26:27]
	v_mad_i64_i32 v[34:35], s[4:5], v34, s87, v[26:27]
	v_add_u32_e32 v25, s18, v25
	global_load_dwordx4 v[8:11], v[8:9], off
	s_nop 0
	global_load_dwordx4 v[12:15], v[12:13], off
	v_lshl_add_u64 v[32:33], v[32:33], 0, v[30:31]
	global_load_dwordx4 v[16:19], v[16:17], off
	v_lshl_add_u64 v[34:35], v[34:35], 0, v[30:31]
	v_lshl_add_u64 v[36:37], v[36:37], 0, v[30:31]
	global_load_dwordx2 v[106:107], v[28:29], off offset:3072 nt
	global_load_dwordx2 v[104:105], v[32:33], off offset:3072 nt
	global_load_dwordx2 v[72:73], v[34:35], off offset:3072 nt
	global_load_dwordx2 v[74:75], v[36:37], off offset:3072 nt
	v_mad_i64_i32 v[28:29], s[4:5], v25, s87, v[26:27]
	v_or_b32_e32 v25, 3, v24
	v_min_i32_e32 v25, s17, v25
	v_cndmask_b32_e64 v25, v25, 0, vcc
	v_add_u32_e32 v25, s18, v25
	v_mad_i64_i32 v[32:33], s[4:5], v25, s87, v[26:27]
	v_or_b32_e32 v25, 4, v24
	v_min_i32_e32 v25, s17, v25
	v_cndmask_b32_e64 v25, v25, 0, vcc
	v_add_u32_e32 v25, s18, v25
	v_mad_i64_i32 v[34:35], s[4:5], v25, s87, v[26:27]
	v_or_b32_e32 v25, 5, v24
	v_min_i32_e32 v25, s17, v25
	v_cndmask_b32_e64 v25, v25, 0, vcc
	v_add_u32_e32 v25, s18, v25
	v_mad_i64_i32 v[36:37], s[4:5], v25, s87, v[26:27]
	v_or_b32_e32 v25, 6, v24
	v_min_i32_e32 v25, s17, v25
	v_cmp_lt_i32_e32 vcc, -7, v24
	v_lshl_add_u64 v[28:29], v[28:29], 0, v[30:31]
	v_lshl_add_u64 v[32:33], v[32:33], 0, v[30:31]
	v_cndmask_b32_e32 v25, 0, v25, vcc
	v_add_u32_e32 v25, s18, v25
	v_lshl_add_u64 v[34:35], v[34:35], 0, v[30:31]
	v_lshl_add_u64 v[36:37], v[36:37], 0, v[30:31]
	global_load_dwordx2 v[84:85], v[28:29], off offset:3072 nt
	global_load_dwordx2 v[86:87], v[32:33], off offset:3072 nt
	global_load_dwordx2 v[88:89], v[34:35], off offset:3072 nt
	global_load_dwordx2 v[90:91], v[36:37], off offset:3072 nt
	v_mad_i64_i32 v[28:29], s[4:5], v25, s87, v[26:27]
	v_or_b32_e32 v25, 7, v24
	v_min_i32_e32 v25, s17, v25
	v_cmp_lt_i32_e32 vcc, -8, v24
	v_lshl_add_u64 v[28:29], v[28:29], 0, v[30:31]
	s_nop 0
	v_cndmask_b32_e32 v25, 0, v25, vcc
	v_add_u32_e32 v25, s18, v25
	v_mad_i64_i32 v[32:33], s[4:5], v25, s87, v[26:27]
	v_add_u32_e32 v25, 8, v24
	v_min_i32_e32 v25, s17, v25
	v_cmp_lt_i32_e32 vcc, -9, v24
	v_lshl_add_u64 v[32:33], v[32:33], 0, v[30:31]
	s_nop 0
	v_cndmask_b32_e32 v25, 0, v25, vcc
	v_add_u32_e32 v25, s18, v25
	v_mad_i64_i32 v[34:35], s[4:5], v25, s87, v[26:27]
	v_add_u32_e32 v25, 9, v24
	v_min_i32_e32 v25, s17, v25
	v_cmp_lt_i32_e32 vcc, -10, v24
	v_lshl_add_u64 v[34:35], v[34:35], 0, v[30:31]
	s_nop 0
	v_cndmask_b32_e32 v25, 0, v25, vcc
	v_add_u32_e32 v25, s18, v25
	v_mad_i64_i32 v[26:27], s[4:5], v25, s87, v[26:27]
	v_lshl_add_u64 v[26:27], v[26:27], 0, v[30:31]
	global_load_dwordx2 v[96:97], v[28:29], off offset:3072 nt
	global_load_dwordx2 v[98:99], v[32:33], off offset:3072 nt
	global_load_dwordx2 v[100:101], v[34:35], off offset:3072 nt
	global_load_dwordx2 v[102:103], v[26:27], off offset:3072 nt
	v_cndmask_b32_e64 v25, 0, 1, s[2:3]
	v_cmp_ne_u32_e64 s[4:5], 1, v25
	s_andn2_b64 vcc, exec, s[2:3]
	s_cbranch_vccnz .LBB0_386
	v_add_u32_e32 v25, 10, v24
	v_min_i32_e32 v25, s17, v25
	v_cmp_lt_i32_e32 vcc, -11, v24
	v_mov_b64_e32 v[26:27], s[76:77]
	s_nop 0
	v_cndmask_b32_e32 v25, 0, v25, vcc
	v_add_u32_e32 v25, s18, v25
	v_mad_i64_i32 v[26:27], s[2:3], v25, s87, v[26:27]
	v_lshl_add_u64 v[26:27], v[20:21], 1, v[26:27]
	global_load_dwordx2 v[68:69], v[26:27], off offset:3072 nt
	s_and_b64 vcc, exec, s[4:5]
	s_cbranch_vccz .LBB0_387

.LBB0_381:
	v_add_u32_e32 v25, 12, v24
	v_min_i32_e32 v25, s17, v25
	v_cmp_lt_i32_e32 vcc, -13, v24
	v_mov_b64_e32 v[26:27], s[76:77]
	s_nop 0
	v_cndmask_b32_e32 v25, 0, v25, vcc
	v_add_u32_e32 v25, s18, v25
	v_mad_i64_i32 v[26:27], s[2:3], v25, s87, v[26:27]
	v_lshl_add_u64 v[26:27], v[20:21], 1, v[26:27]
	global_load_dwordx2 v[76:77], v[26:27], off offset:3072 nt
	s_and_b64 vcc, exec, s[4:5]
	s_cbranch_vccz .LBB0_389

.LBB0_383:
	v_add_u32_e32 v25, 14, v24
	v_min_i32_e32 v25, s17, v25
	v_cmp_lt_i32_e32 vcc, -15, v24
	v_mov_b64_e32 v[26:27], s[76:77]
	s_nop 0
	v_cndmask_b32_e32 v25, 0, v25, vcc
	v_add_u32_e32 v25, s18, v25
	v_mad_i64_i32 v[26:27], s[2:3], v25, s87, v[26:27]
	v_lshl_add_u64 v[26:27], v[20:21], 1, v[26:27]
	global_load_dwordx2 v[80:81], v[26:27], off offset:3072 nt
	s_and_b64 vcc, exec, s[4:5]
	s_cbranch_vccz .LBB0_391

.LBB0_385:
	v_add_u32_e32 v25, 16, v24
	s_movk_i32 s2, 0xffef
	v_min_i32_e32 v25, s17, v25
	v_cmp_lt_i32_e32 vcc, s2, v24
	v_mov_b64_e32 v[26:27], s[76:77]
	s_nop 0
	v_cndmask_b32_e32 v25, 0, v25, vcc
	v_add_u32_e32 v25, s18, v25
	v_mad_i64_i32 v[26:27], s[2:3], v25, s87, v[26:27]
	v_lshl_add_u64 v[26:27], v[20:21], 1, v[26:27]
	global_load_dwordx2 v[92:93], v[26:27], off offset:3072 nt
	s_and_b64 vcc, exec, s[4:5]
	s_cbranch_vccz .LBB0_393
	s_branch .LBB0_394

.LBB0_387:
	v_add_u32_e32 v25, 11, v24
	v_min_i32_e32 v25, s17, v25
	v_cmp_lt_i32_e32 vcc, -12, v24
	v_mov_b64_e32 v[26:27], s[76:77]
	s_nop 0
	v_cndmask_b32_e32 v25, 0, v25, vcc
	v_add_u32_e32 v25, s18, v25
	v_mad_i64_i32 v[26:27], s[2:3], v25, s87, v[26:27]
	v_lshl_add_u64 v[26:27], v[20:21], 1, v[26:27]
	global_load_dwordx2 v[70:71], v[26:27], off offset:3072 nt
	s_and_b64 vcc, exec, s[4:5]
	s_cbranch_vccz .LBB0_381

.LBB0_389:
	v_add_u32_e32 v25, 13, v24
	v_min_i32_e32 v25, s17, v25
	v_cmp_lt_i32_e32 vcc, -14, v24
	v_mov_b64_e32 v[26:27], s[76:77]
	s_nop 0
	v_cndmask_b32_e32 v25, 0, v25, vcc
	v_add_u32_e32 v25, s18, v25
	v_mad_i64_i32 v[26:27], s[2:3], v25, s87, v[26:27]
	v_lshl_add_u64 v[26:27], v[20:21], 1, v[26:27]
	global_load_dwordx2 v[78:79], v[26:27], off offset:3072 nt
	s_and_b64 vcc, exec, s[4:5]
	s_cbranch_vccz .LBB0_383

.LBB0_391:
	v_add_u32_e32 v25, 15, v24
	v_min_i32_e32 v25, s17, v25
	v_cmp_lt_i32_e32 vcc, -16, v24
	v_mov_b64_e32 v[26:27], s[76:77]
	s_nop 0
	v_cndmask_b32_e32 v25, 0, v25, vcc
	v_add_u32_e32 v25, s18, v25
	v_mad_i64_i32 v[26:27], s[2:3], v25, s87, v[26:27]
	v_lshl_add_u64 v[26:27], v[20:21], 1, v[26:27]
	global_load_dwordx2 v[82:83], v[26:27], off offset:3072 nt
	s_and_b64 vcc, exec, s[4:5]
	s_cbranch_vccz .LBB0_385

.LBB0_393:
	v_add_u32_e32 v25, 17, v24
	s_movk_i32 s2, 0xffee
	v_min_i32_e32 v25, s17, v25
	v_cmp_lt_i32_e32 vcc, s2, v24
	s_nop 1
	v_cndmask_b32_e32 v24, 0, v25, vcc
	v_add_u32_e32 v26, s18, v24
	v_mov_b64_e32 v[24:25], s[76:77]
	v_mad_i64_i32 v[24:25], s[2:3], v26, s87, v[24:25]
	v_lshl_add_u64 v[20:21], v[20:21], 1, v[24:25]
	global_load_dwordx2 v[94:95], v[20:21], off offset:3072 nt

; #define LDS_BARRIER() asm volatile("s_waitcnt lgkmcnt(0)\n\ts_barrier" ::: "memory")
; __device__ __forceinline__ void gdn_prep_phase(const Frame& F0, const Args& a0, int l) {
;     ...
;         LDS_BARRIER();
;         if (u + F.G < NB * 8 * 36) GD_PREFETCH(u + F.G);
.LBB0_420:
	s_add_i32 s27, s27, s22
	s_cmpk_lt_i32 s27, 0x480
	s_waitcnt lgkmcnt(0)
	s_barrier
	s_cselect_b64 s[12:13], -1, 0
	s_cmpk_gt_i32 s27, 0x47f
	s_cselect_b64 s[68:69], -1, 0
	v_cndmask_b32_e64 v20, 0, 1, s[2:3]
	s_and_b64 vcc, exec, s[68:69]
	v_cmp_ne_u32_e64 s[8:9], 1, v20
	s_cbranch_vccnz .LBB0_438
	s_mul_hi_i32 s11, s27, 0x38e38e39
	s_ashr_i32 s10, s11, 3
	s_lshr_b32 s14, s11, 31
	s_add_i32 s53, s10, s14
	s_mul_i32 s10, s53, 0xffffffdc
	v_mbcnt_lo_u32_b32 v22, -1, 0
	v_mbcnt_hi_u32_b32 v22, -1, v22
	s_add_i32 s15, s27, s10
	v_ashrrev_i32_e32 v0, 5, v22
	s_and_b32 s10, s53, 7
	s_lshr_b32 s11, s11, 6
	v_add_lshl_u32 v23, v0, s73, 3
	v_lshlrev_b32_e32 v0, 10, v0
	v_lshlrev_b32_e32 v1, 2, v22
	s_add_i32 s54, s11, s14
	s_mul_i32 s14, s53, 0xfffff700
	s_add_i32 s11, s49, s45
	s_lshl_b32 s56, s10, 7
	v_cndmask_b32_e64 v0, v188, v0, s[2:3]
	v_and_b32_e32 v1, 0x7c, v1
	s_add_i32 s55, s11, s14
	v_or3_b32 v20, v0, s56, v1
	s_add_i32 s57, s55, 0xffffff00
	v_ashrrev_i32_e32 v21, 31, v20
	s_cmp_lt_i32 s15, 4
	v_lshl_add_u64 v[16:17], v[20:21], 2, s[62:63]
	s_movk_i32 s15, 0x3000
	v_add_co_u32_e32 v4, vcc, s15, v16
	s_movk_i32 s15, 0x6000
	s_nop 0
	v_addc_co_u32_e32 v5, vcc, 0, v17, vcc
	v_add_co_u32_e32 v8, vcc, s15, v16
	s_mov_b32 s15, 0x9000
	s_nop 0
	v_addc_co_u32_e32 v9, vcc, 0, v17, vcc
	v_add_co_u32_e32 v12, vcc, s15, v16
	s_mov_b32 s15, 0xc000
	s_nop 0
	v_addc_co_u32_e32 v13, vcc, 0, v17, vcc
	v_mov_b32_e32 v24, s25
	global_load_dwordx4 v[0:3], v[16:17], off
	s_nop 0
	global_load_dwordx4 v[4:7], v[4:5], off
	v_add_co_u32_e32 v16, vcc, s15, v16
	s_mul_i32 s15, s54, 0x900
	s_cselect_b32 s54, s55, s57
	v_cndmask_b32_e64 v23, v23, v24, s[2:3]
	s_movk_i32 s14, 0x7ff
	v_add_u32_e32 v23, s54, v23
	s_cselect_b32 s14, 0xff, s14
	v_addc_co_u32_e32 v17, vcc, 0, v17, vcc
	v_add_u32_e32 v24, -2, v23
	v_min_i32_e32 v24, s14, v24
	v_cmp_lt_i32_e32 vcc, 1, v23
	v_or_b32_e32 v34, 1, v23
	v_add_u32_e32 v30, -1, v23
	v_cndmask_b32_e32 v24, 0, v24, vcc
	v_min_i32_e32 v30, s14, v30
	v_cmp_lt_i32_e32 vcc, 1, v34
	v_min_i32_e32 v32, s14, v23
	v_min_i32_e32 v34, s14, v34
	v_cndmask_b32_e32 v30, 0, v30, vcc
	v_cmp_gt_i32_e32 vcc, 0, v23
	v_add_u32_e32 v24, s15, v24
	v_subrev_u32_e32 v24, s54, v24
	v_cndmask_b32_e64 v32, v32, 0, vcc
	v_cndmask_b32_e64 v34, v34, 0, vcc
	s_mulk_i32 s53, 0x900
	v_add_u32_e32 v30, s15, v30
	v_add_u32_e32 v32, s15, v32
	v_add_u32_e32 v34, s15, v34
	v_subrev_u32_e32 v24, s53, v24
	v_subrev_u32_e32 v30, s54, v30
	v_subrev_u32_e32 v32, s54, v32
	v_subrev_u32_e32 v34, s54, v34
	v_add_u32_e32 v26, s11, v24
	v_mov_b64_e32 v[24:25], s[76:77]
	v_subrev_u32_e32 v30, s53, v30
	v_subrev_u32_e32 v32, s53, v32
	v_subrev_u32_e32 v34, s53, v34
	v_mad_i64_i32 v[26:27], s[56:57], v26, s87, v[24:25]
	v_lshlrev_b64 v[28:29], 1, v[20:21]
	v_add_u32_e32 v30, s11, v30
	v_add_u32_e32 v32, s11, v32
	v_add_u32_e32 v34, s11, v34
	v_lshl_add_u64 v[26:27], v[26:27], 0, v[28:29]
	v_mad_i64_i32 v[30:31], s[56:57], v30, s87, v[24:25]
	v_mad_i64_i32 v[32:33], s[56:57], v32, s87, v[24:25]
	v_mad_i64_i32 v[34:35], s[56:57], v34, s87, v[24:25]
	global_load_dwordx4 v[8:11], v[8:9], off
	s_nop 0
	global_load_dwordx4 v[12:15], v[12:13], off
	v_lshl_add_u64 v[30:31], v[30:31], 0, v[28:29]
	global_load_dwordx4 v[16:19], v[16:17], off
	v_lshl_add_u64 v[32:33], v[32:33], 0, v[28:29]
	v_lshl_add_u64 v[34:35], v[34:35], 0, v[28:29]
	global_load_dwordx2 v[64:65], v[26:27], off offset:3072 nt
	global_load_dwordx2 v[66:67], v[30:31], off offset:3072 nt
	global_load_dwordx2 v[72:73], v[32:33], off offset:3072 nt
	global_load_dwordx2 v[74:75], v[34:35], off offset:3072 nt
	v_or_b32_e32 v26, 2, v23
	v_min_i32_e32 v26, s14, v26
	v_or_b32_e32 v30, 3, v23
	v_or_b32_e32 v32, 4, v23
	v_or_b32_e32 v34, 5, v23
	v_cndmask_b32_e64 v26, v26, 0, vcc
	v_min_i32_e32 v30, s14, v30
	v_min_i32_e32 v32, s14, v32
	v_min_i32_e32 v34, s14, v34
	v_add_u32_e32 v26, s15, v26
	v_cndmask_b32_e64 v30, v30, 0, vcc
	v_cndmask_b32_e64 v32, v32, 0, vcc
	v_cndmask_b32_e64 v34, v34, 0, vcc
	v_subrev_u32_e32 v26, s54, v26
	v_add_u32_e32 v30, s15, v30
	v_add_u32_e32 v32, s15, v32
	v_add_u32_e32 v34, s15, v34
	v_subrev_u32_e32 v26, s53, v26
	v_subrev_u32_e32 v30, s54, v30
	v_subrev_u32_e32 v32, s54, v32
	v_subrev_u32_e32 v34, s54, v34
	v_add_u32_e32 v26, s11, v26
	v_subrev_u32_e32 v30, s53, v30
	v_subrev_u32_e32 v32, s53, v32
	v_subrev_u32_e32 v34, s53, v34
	v_mad_i64_i32 v[26:27], s[56:57], v26, s87, v[24:25]
	v_add_u32_e32 v30, s11, v30
	v_add_u32_e32 v32, s11, v32
	v_add_u32_e32 v34, s11, v34
	v_lshl_add_u64 v[26:27], v[26:27], 0, v[28:29]
	v_mad_i64_i32 v[30:31], s[56:57], v30, s87, v[24:25]
	v_mad_i64_i32 v[32:33], s[56:57], v32, s87, v[24:25]
	v_mad_i64_i32 v[34:35], s[56:57], v34, s87, v[24:25]
	v_lshl_add_u64 v[30:31], v[30:31], 0, v[28:29]
	v_lshl_add_u64 v[32:33], v[32:33], 0, v[28:29]
	v_lshl_add_u64 v[34:35], v[34:35], 0, v[28:29]
	global_load_dwordx2 v[84:85], v[26:27], off offset:3072 nt
	global_load_dwordx2 v[86:87], v[30:31], off offset:3072 nt
	global_load_dwordx2 v[88:89], v[32:33], off offset:3072 nt
	global_load_dwordx2 v[90:91], v[34:35], off offset:3072 nt
	v_or_b32_e32 v26, 6, v23
	v_min_i32_e32 v26, s14, v26
	v_cmp_lt_i32_e32 vcc, -7, v23
	v_or_b32_e32 v30, 7, v23
	v_min_i32_e32 v30, s14, v30
	v_cndmask_b32_e32 v26, 0, v26, vcc
	v_cmp_lt_i32_e32 vcc, -8, v23
	v_add_u32_e32 v32, 8, v23
	v_min_i32_e32 v32, s14, v32
	v_cndmask_b32_e32 v30, 0, v30, vcc
	v_cmp_lt_i32_e32 vcc, -9, v23
	v_add_u32_e32 v34, 9, v23
	v_min_i32_e32 v34, s14, v34
	v_cndmask_b32_e32 v32, 0, v32, vcc
	v_cmp_lt_i32_e32 vcc, -10, v23
	v_add_u32_e32 v26, s15, v26
	v_subrev_u32_e32 v26, s54, v26
	v_cndmask_b32_e32 v34, 0, v34, vcc
	v_add_u32_e32 v30, s15, v30
	v_add_u32_e32 v32, s15, v32
	v_add_u32_e32 v34, s15, v34
	v_subrev_u32_e32 v26, s53, v26
	v_subrev_u32_e32 v30, s54, v30
	v_subrev_u32_e32 v32, s54, v32
	v_subrev_u32_e32 v34, s54, v34
	v_add_u32_e32 v26, s11, v26
	v_subrev_u32_e32 v30, s53, v30
	v_subrev_u32_e32 v32, s53, v32
	v_subrev_u32_e32 v34, s53, v34
	v_mad_i64_i32 v[26:27], s[56:57], v26, s87, v[24:25]
	v_add_u32_e32 v30, s11, v30
	v_add_u32_e32 v32, s11, v32
	v_add_u32_e32 v34, s11, v34
	v_lshl_add_u64 v[26:27], v[26:27], 0, v[28:29]
	v_mad_i64_i32 v[30:31], s[56:57], v30, s87, v[24:25]
	v_mad_i64_i32 v[32:33], s[56:57], v32, s87, v[24:25]
	v_mad_i64_i32 v[24:25], s[56:57], v34, s87, v[24:25]
	v_lshl_add_u64 v[30:31], v[30:31], 0, v[28:29]
	v_lshl_add_u64 v[32:33], v[32:33], 0, v[28:29]
	v_lshl_add_u64 v[24:25], v[24:25], 0, v[28:29]
	global_load_dwordx2 v[96:97], v[26:27], off offset:3072 nt
	global_load_dwordx2 v[98:99], v[30:31], off offset:3072 nt
	global_load_dwordx2 v[100:101], v[32:33], off offset:3072 nt
	global_load_dwordx2 v[102:103], v[24:25], off offset:3072 nt
	s_and_b64 vcc, exec, s[8:9]
	s_cbranch_vccnz .LBB0_429
	v_add_u32_e32 v24, 10, v23
	v_min_i32_e32 v24, s14, v24
	v_cmp_lt_i32_e32 vcc, -11, v23
	s_nop 1
	v_cndmask_b32_e32 v24, 0, v24, vcc
	v_add_u32_e32 v24, s15, v24
	v_subrev_u32_e32 v24, s54, v24
	v_subrev_u32_e32 v24, s53, v24
	v_add_u32_e32 v26, s11, v24
	v_mov_b64_e32 v[24:25], s[76:77]
	v_mad_i64_i32 v[24:25], s[56:57], v26, s87, v[24:25]
	v_lshl_add_u64 v[24:25], v[20:21], 1, v[24:25]
	global_load_dwordx2 v[68:69], v[24:25], off offset:3072 nt
	s_and_b64 vcc, exec, s[8:9]
	s_cbranch_vccz .LBB0_430

.LBB0_424:
	v_add_u32_e32 v24, 12, v23
	v_min_i32_e32 v24, s14, v24
	v_cmp_lt_i32_e32 vcc, -13, v23
	s_nop 1
	v_cndmask_b32_e32 v24, 0, v24, vcc
	v_add_u32_e32 v24, s15, v24
	v_subrev_u32_e32 v24, s54, v24
	v_subrev_u32_e32 v24, s53, v24
	v_add_u32_e32 v26, s11, v24
	v_mov_b64_e32 v[24:25], s[76:77]
	v_mad_i64_i32 v[24:25], s[56:57], v26, s87, v[24:25]
	v_lshl_add_u64 v[24:25], v[20:21], 1, v[24:25]
	global_load_dwordx2 v[76:77], v[24:25], off offset:3072 nt
	s_and_b64 vcc, exec, s[8:9]
	s_cbranch_vccz .LBB0_432

.LBB0_426:
	v_add_u32_e32 v24, 14, v23
	v_min_i32_e32 v24, s14, v24
	v_cmp_lt_i32_e32 vcc, -15, v23
	s_nop 1
	v_cndmask_b32_e32 v24, 0, v24, vcc
	v_add_u32_e32 v24, s15, v24
	v_subrev_u32_e32 v24, s54, v24
	v_subrev_u32_e32 v24, s53, v24
	v_add_u32_e32 v26, s11, v24
	v_mov_b64_e32 v[24:25], s[76:77]
	v_mad_i64_i32 v[24:25], s[56:57], v26, s87, v[24:25]
	v_lshl_add_u64 v[24:25], v[20:21], 1, v[24:25]
	global_load_dwordx2 v[80:81], v[24:25], off offset:3072 nt
	s_and_b64 vcc, exec, s[8:9]
	s_cbranch_vccz .LBB0_434

.LBB0_428:
	v_add_u32_e32 v24, 16, v23
	s_movk_i32 s55, 0xffef
	v_min_i32_e32 v24, s14, v24
	v_cmp_lt_i32_e32 vcc, s55, v23
	s_nop 1
	v_cndmask_b32_e32 v24, 0, v24, vcc
	v_add_u32_e32 v24, s15, v24
	v_subrev_u32_e32 v24, s54, v24
	v_subrev_u32_e32 v24, s53, v24
	v_add_u32_e32 v26, s11, v24
	v_mov_b64_e32 v[24:25], s[76:77]
	v_mad_i64_i32 v[24:25], s[56:57], v26, s87, v[24:25]
	v_lshl_add_u64 v[24:25], v[20:21], 1, v[24:25]
	global_load_dwordx2 v[92:93], v[24:25], off offset:3072 nt
	s_and_b64 vcc, exec, s[8:9]
	s_cbranch_vccz .LBB0_436
	s_branch .LBB0_437

.LBB0_430:
	v_add_u32_e32 v24, 11, v23
	v_min_i32_e32 v24, s14, v24
	v_cmp_lt_i32_e32 vcc, -12, v23
	s_nop 1
	v_cndmask_b32_e32 v24, 0, v24, vcc
	v_add_u32_e32 v24, s15, v24
	v_subrev_u32_e32 v24, s54, v24
	v_subrev_u32_e32 v24, s53, v24
	v_add_u32_e32 v26, s11, v24
	v_mov_b64_e32 v[24:25], s[76:77]
	v_mad_i64_i32 v[24:25], s[56:57], v26, s87, v[24:25]
	v_lshl_add_u64 v[24:25], v[20:21], 1, v[24:25]
	global_load_dwordx2 v[70:71], v[24:25], off offset:3072 nt
	s_and_b64 vcc, exec, s[8:9]
	s_cbranch_vccz .LBB0_424

.LBB0_432:
	v_add_u32_e32 v24, 13, v23
	v_min_i32_e32 v24, s14, v24
	v_cmp_lt_i32_e32 vcc, -14, v23
	s_nop 1
	v_cndmask_b32_e32 v24, 0, v24, vcc
	v_add_u32_e32 v24, s15, v24
	v_subrev_u32_e32 v24, s54, v24
	v_subrev_u32_e32 v24, s53, v24
	v_add_u32_e32 v26, s11, v24
	v_mov_b64_e32 v[24:25], s[76:77]
	v_mad_i64_i32 v[24:25], s[56:57], v26, s87, v[24:25]
	v_lshl_add_u64 v[24:25], v[20:21], 1, v[24:25]
	global_load_dwordx2 v[78:79], v[24:25], off offset:3072 nt
	s_and_b64 vcc, exec, s[8:9]
	s_cbranch_vccz .LBB0_426

.LBB0_434:
	v_add_u32_e32 v24, 15, v23
	v_min_i32_e32 v24, s14, v24
	v_cmp_lt_i32_e32 vcc, -16, v23
	s_nop 1
	v_cndmask_b32_e32 v24, 0, v24, vcc
	v_add_u32_e32 v24, s15, v24
	v_subrev_u32_e32 v24, s54, v24
	v_subrev_u32_e32 v24, s53, v24
	v_add_u32_e32 v26, s11, v24
	v_mov_b64_e32 v[24:25], s[76:77]
	v_mad_i64_i32 v[24:25], s[56:57], v26, s87, v[24:25]
	v_lshl_add_u64 v[24:25], v[20:21], 1, v[24:25]
	global_load_dwordx2 v[82:83], v[24:25], off offset:3072 nt
	s_and_b64 vcc, exec, s[8:9]
	s_cbranch_vccz .LBB0_428

.LBB0_436:
	v_add_u32_e32 v24, 17, v23
	v_min_i32_e32 v24, s14, v24
	s_movk_i32 s14, 0xffee
	v_cmp_lt_i32_e32 vcc, s14, v23
	s_nop 1
	v_cndmask_b32_e32 v23, 0, v24, vcc
	v_add_u32_e32 v23, s15, v23
	v_subrev_u32_e32 v23, s54, v23
	v_subrev_u32_e32 v23, s53, v23
	v_add_u32_e32 v23, s11, v23
	v_mov_b64_e32 v[24:25], s[76:77]
	v_mad_i64_i32 v[24:25], s[54:55], v23, s87, v[24:25]
	v_lshl_add_u64 v[20:21], v[20:21], 1, v[24:25]
	global_load_dwordx2 v[94:95], v[20:21], off offset:3072 nt
